# combine chain: waves 0-3 issue the step's LDS operand reads right after the barrier, before the next-step P-image writes and refill loads
# baseline (speedup 1.0000x reference)
; __device__ __forceinline__ void phase_combine(const Params& p, LAS unsigned char* lds, int tid, int lane, int wave, bool dummy) {
;     ...
;             for (int seg0 = 0; seg0 < 126; seg0 += 6) {
;                 CB_STEP(seg0 + 0, 0, true); CB_STEP(seg0 + 1, 1, true); CB_STEP(seg0 + 2, 2, true);
;                 CB_STEP(seg0 + 3, 3, true); CB_STEP(seg0 + 4, 4, true); CB_STEP(seg0 + 5, 5, true);
;             }
.LBB0_498:
	s_add_i32 s12, s12, 6
	s_min_u32 s2, s12, 0x77
	s_mulk_i32 s2, 0x6000
	s_lshl_b32 s72, s2, 2
	s_andn2_b64 vcc, exec, s[8:9]
	s_cbranch_vccnz .Lmy_cbw_498
	ds_read2st64_b32 v[200:201], v175 offset1:4
	ds_read2st64_b32 v[216:217], v176 offset0:128 offset1:129
	ds_read2st64_b32 v[202:203], v175 offset0:8 offset1:12
	ds_read2st64_b32 v[218:219], v176 offset0:130 offset1:131
	ds_read2st64_b32 v[204:205], v175 offset0:16 offset1:20
	ds_read2st64_b32 v[220:221], v176 offset0:132 offset1:133
	ds_read2st64_b32 v[206:207], v175 offset0:24 offset1:28
	ds_read2st64_b32 v[222:223], v176 offset0:134 offset1:135
	ds_read2st64_b32 v[208:209], v175 offset0:32 offset1:36
	ds_read2st64_b32 v[224:225], v176 offset0:136 offset1:137
	ds_read2st64_b32 v[210:211], v175 offset0:40 offset1:44
	ds_read2st64_b32 v[226:227], v176 offset0:138 offset1:139
	s_waitcnt vmcnt(15)
	ds_write_b128 v81, v[6:9] offset:16384
	ds_write_b128 v81, v[2:5] offset:16400
	v_lshl_add_u64 v[2:3], v[90:91], 0, s[72:73]
	s_mov_b64 s[6:7], 0xa8000
	v_lshl_add_u64 v[4:5], v[2:3], 0, s[6:7]
	v_add_co_u32_e32 v2, vcc, 0xa8000, v2
	v_cndmask_b32_e64 v0, 0, 1, s[8:9]
	s_nop 0
	v_addc_co_u32_e32 v3, vcc, 0, v3, vcc
	v_add_co_u32_e32 v50, vcc, 0x90000, v92
	global_load_dwordx4 v[6:9], v[2:3], off
	s_nop 0
	global_load_dwordx4 v[2:5], v[4:5], off offset:16
	v_addc_co_u32_e32 v51, vcc, 0, v93, vcc
	global_load_dwordx4 v[50:53], v[50:51], off
	v_cmp_ne_u32_e64 s[6:7], 1, v0
	v_add_u32_e32 v0, 0x9000, v179
	s_waitcnt lgkmcnt(12)
	v_mfma_f32_16x16x4_f32 v[58:61], v200, v216, v[58:61]
	v_mfma_f32_16x16x4_f32 v[94:97], v201, v217, 0
	ds_read2st64_b32 v[212:213], v175 offset0:48 offset1:52
	ds_read2st64_b32 v[228:229], v176 offset0:140 offset1:141
	s_waitcnt lgkmcnt(12)
	v_mfma_f32_16x16x4_f32 v[58:61], v202, v218, v[58:61]
	v_mfma_f32_16x16x4_f32 v[94:97], v203, v219, v[94:97]
	ds_read2st64_b32 v[214:215], v175 offset0:56 offset1:60
	ds_read2st64_b32 v[230:231], v176 offset0:142 offset1:143
	s_waitcnt lgkmcnt(12)
	v_mfma_f32_16x16x4_f32 v[58:61], v204, v220, v[58:61]
	v_mfma_f32_16x16x4_f32 v[94:97], v205, v221, v[94:97]
	s_waitcnt lgkmcnt(10)
	v_mfma_f32_16x16x4_f32 v[58:61], v206, v222, v[58:61]
	v_mfma_f32_16x16x4_f32 v[94:97], v207, v223, v[94:97]
	s_waitcnt lgkmcnt(8)
	v_mfma_f32_16x16x4_f32 v[58:61], v208, v224, v[58:61]
	v_mfma_f32_16x16x4_f32 v[94:97], v209, v225, v[94:97]
	s_waitcnt lgkmcnt(6)
	v_mfma_f32_16x16x4_f32 v[58:61], v210, v226, v[58:61]
	v_mfma_f32_16x16x4_f32 v[94:97], v211, v227, v[94:97]
	s_waitcnt lgkmcnt(2)
	v_mfma_f32_16x16x4_f32 v[58:61], v212, v228, v[58:61]
	v_mfma_f32_16x16x4_f32 v[94:97], v213, v229, v[94:97]
	s_waitcnt lgkmcnt(0)
	v_mfma_f32_16x16x4_f32 v[58:61], v214, v230, v[58:61]
	v_mfma_f32_16x16x4_f32 v[94:97], v215, v231, v[94:97]
	s_nop 9
	v_pk_add_f32 v[60:61], v[60:61], v[96:97]
	v_pk_add_f32 v[58:59], v[58:59], v[94:95]
	global_store_dwordx4 v[92:93], v[58:61], off
	ds_write2_b32 v0, v58, v59 offset1:16
	ds_write2_b32 v0, v60, v61 offset0:32 offset1:48
	s_branch .LBB0_500
.Lmy_cbw_498:
	s_waitcnt vmcnt(15)
	ds_write_b128 v81, v[6:9] offset:16384
	ds_write_b128 v81, v[2:5] offset:16400
	v_lshl_add_u64 v[2:3], v[90:91], 0, s[72:73]
	s_mov_b64 s[6:7], 0xa8000
	v_lshl_add_u64 v[4:5], v[2:3], 0, s[6:7]
	v_add_co_u32_e32 v2, vcc, 0xa8000, v2
	v_cndmask_b32_e64 v0, 0, 1, s[8:9]
	s_nop 0
	v_addc_co_u32_e32 v3, vcc, 0, v3, vcc
	v_add_co_u32_e32 v50, vcc, 0x90000, v92
	global_load_dwordx4 v[6:9], v[2:3], off
	s_nop 0
	global_load_dwordx4 v[2:5], v[4:5], off offset:16
	v_addc_co_u32_e32 v51, vcc, 0, v93, vcc
	global_load_dwordx4 v[50:53], v[50:51], off
	v_cmp_ne_u32_e64 s[6:7], 1, v0
.LBB0_500:
	s_min_u32 s2, s12, 0x76
	s_mulk_i32 s2, 0x6000
	s_lshl_b32 s10, s2, 2
	s_mov_b32 s11, s73
	s_waitcnt lgkmcnt(0)
	s_barrier
	s_and_b64 vcc, exec, s[6:7]
	s_cbranch_vccnz .Lmy_cbw_500
	ds_read2st64_b32 v[200:201], v175 offset0:64 offset1:68
	ds_read2st64_b32 v[216:217], v176 offset0:144 offset1:145
	ds_read2st64_b32 v[202:203], v175 offset0:72 offset1:76
	ds_read2st64_b32 v[218:219], v176 offset0:146 offset1:147
	ds_read2st64_b32 v[204:205], v175 offset0:80 offset1:84
	ds_read2st64_b32 v[220:221], v176 offset0:148 offset1:149
	ds_read2st64_b32 v[206:207], v175 offset0:88 offset1:92
	ds_read2st64_b32 v[222:223], v176 offset0:150 offset1:151
	ds_read2st64_b32 v[208:209], v175 offset0:96 offset1:100
	ds_read2st64_b32 v[224:225], v176 offset0:152 offset1:153
	ds_read2st64_b32 v[210:211], v175 offset0:104 offset1:108
	ds_read2st64_b32 v[226:227], v176 offset0:154 offset1:155
	s_waitcnt vmcnt(16)
	ds_write_b128 v81, v[14:17]
	ds_write_b128 v81, v[10:13] offset:16
	v_lshl_add_u64 v[10:11], v[90:91], 0, s[10:11]
	s_mov_b64 s[16:17], 0xc0000
	v_lshl_add_u64 v[12:13], v[10:11], 0, s[16:17]
	v_add_co_u32_e32 v10, vcc, 0xc0000, v10
	v_lshl_add_u64 v[58:59], v[88:89], 0, s[72:73]
	s_nop 0
	v_addc_co_u32_e32 v11, vcc, 0, v11, vcc
	v_add_co_u32_e32 v58, vcc, 0xa8000, v58
	global_load_dwordx4 v[14:17], v[10:11], off
	s_nop 0
	global_load_dwordx4 v[10:13], v[12:13], off offset:16
	v_addc_co_u32_e32 v59, vcc, 0, v59, vcc
	global_load_dwordx4 v[58:61], v[58:59], off
	v_add_u32_e32 v0, 0x8000, v179
	s_waitcnt vmcnt(18) lgkmcnt(12)
	v_mfma_f32_16x16x4_f32 v[66:69], v200, v216, v[66:69]
	v_mfma_f32_16x16x4_f32 v[94:97], v201, v217, 0
	ds_read2st64_b32 v[212:213], v175 offset0:112 offset1:116
	ds_read2st64_b32 v[228:229], v176 offset0:156 offset1:157
	s_waitcnt lgkmcnt(12)
	v_mfma_f32_16x16x4_f32 v[66:69], v202, v218, v[66:69]
	v_mfma_f32_16x16x4_f32 v[94:97], v203, v219, v[94:97]
	ds_read2st64_b32 v[214:215], v175 offset0:120 offset1:124
	ds_read2st64_b32 v[230:231], v176 offset0:158 offset1:159
	s_waitcnt lgkmcnt(12)
	v_mfma_f32_16x16x4_f32 v[66:69], v204, v220, v[66:69]
	v_mfma_f32_16x16x4_f32 v[94:97], v205, v221, v[94:97]
	s_waitcnt lgkmcnt(10)
	v_mfma_f32_16x16x4_f32 v[66:69], v206, v222, v[66:69]
	v_mfma_f32_16x16x4_f32 v[94:97], v207, v223, v[94:97]
	s_waitcnt lgkmcnt(8)
	v_mfma_f32_16x16x4_f32 v[66:69], v208, v224, v[66:69]
	v_mfma_f32_16x16x4_f32 v[94:97], v209, v225, v[94:97]
	s_waitcnt lgkmcnt(6)
	v_mfma_f32_16x16x4_f32 v[66:69], v210, v226, v[66:69]
	v_mfma_f32_16x16x4_f32 v[94:97], v211, v227, v[94:97]
	s_waitcnt lgkmcnt(2)
	v_mfma_f32_16x16x4_f32 v[66:69], v212, v228, v[66:69]
	v_mfma_f32_16x16x4_f32 v[94:97], v213, v229, v[94:97]
	s_waitcnt lgkmcnt(0)
	v_mfma_f32_16x16x4_f32 v[66:69], v214, v230, v[66:69]
	v_mfma_f32_16x16x4_f32 v[94:97], v215, v231, v[94:97]
	s_nop 9
	v_pk_add_f32 v[66:67], v[66:67], v[94:95]
	v_add_co_u32_e32 v94, vcc, 0x18000, v92
	v_pk_add_f32 v[68:69], v[68:69], v[96:97]
	s_nop 0
	v_addc_co_u32_e32 v95, vcc, 0, v93, vcc
	global_store_dwordx4 v[94:95], v[66:69], off
	ds_write2_b32 v0, v66, v67 offset1:16
	ds_write2_b32 v0, v68, v69 offset0:32 offset1:48
	s_branch .LBB0_502
.Lmy_cbw_500:
	s_waitcnt vmcnt(16)
	ds_write_b128 v81, v[14:17]
	ds_write_b128 v81, v[10:13] offset:16
	v_lshl_add_u64 v[10:11], v[90:91], 0, s[10:11]
	s_mov_b64 s[16:17], 0xc0000
	v_lshl_add_u64 v[12:13], v[10:11], 0, s[16:17]
	v_add_co_u32_e32 v10, vcc, 0xc0000, v10
	v_lshl_add_u64 v[58:59], v[88:89], 0, s[72:73]
	s_nop 0
	v_addc_co_u32_e32 v11, vcc, 0, v11, vcc
	v_add_co_u32_e32 v58, vcc, 0xa8000, v58
	global_load_dwordx4 v[14:17], v[10:11], off
	s_nop 0
	global_load_dwordx4 v[10:13], v[12:13], off offset:16
	v_addc_co_u32_e32 v59, vcc, 0, v59, vcc
	global_load_dwordx4 v[58:61], v[58:59], off
.LBB0_502:
	s_min_u32 s2, s12, 0x75
	s_mulk_i32 s2, 0x6000
	s_lshl_b32 s72, s2, 2
	s_waitcnt lgkmcnt(0)
	s_barrier
	s_and_b64 vcc, exec, s[6:7]
	s_cbranch_vccnz .Lmy_cbw_502
	ds_read2st64_b32 v[200:201], v175 offset1:4
	ds_read2st64_b32 v[216:217], v176 offset0:128 offset1:129
	ds_read2st64_b32 v[202:203], v175 offset0:8 offset1:12
	ds_read2st64_b32 v[218:219], v176 offset0:130 offset1:131
	ds_read2st64_b32 v[204:205], v175 offset0:16 offset1:20
	ds_read2st64_b32 v[220:221], v176 offset0:132 offset1:133
	ds_read2st64_b32 v[206:207], v175 offset0:24 offset1:28
	ds_read2st64_b32 v[222:223], v176 offset0:134 offset1:135
	ds_read2st64_b32 v[208:209], v175 offset0:32 offset1:36
	ds_read2st64_b32 v[224:225], v176 offset0:136 offset1:137
	ds_read2st64_b32 v[210:211], v175 offset0:40 offset1:44
	ds_read2st64_b32 v[226:227], v176 offset0:138 offset1:139
	s_waitcnt vmcnt(17)
	ds_write_b128 v81, v[18:21] offset:16384
	s_waitcnt vmcnt(16)
	ds_write_b128 v81, v[22:25] offset:16400
	v_lshl_add_u64 v[18:19], v[90:91], 0, s[72:73]
	s_mov_b64 s[16:17], 0xd8000
	v_lshl_add_u64 v[22:23], v[18:19], 0, s[16:17]
	v_add_co_u32_e32 v18, vcc, 0xd8000, v18
	v_lshl_add_u64 v[66:67], v[88:89], 0, s[10:11]
	s_nop 0
	v_addc_co_u32_e32 v19, vcc, 0, v19, vcc
	v_add_co_u32_e32 v66, vcc, 0xc0000, v66
	global_load_dwordx4 v[18:21], v[18:19], off
	s_nop 0
	global_load_dwordx4 v[22:25], v[22:23], off offset:16
	v_addc_co_u32_e32 v67, vcc, 0, v67, vcc
	global_load_dwordx4 v[66:69], v[66:67], off
	s_waitcnt vmcnt(18) lgkmcnt(12)
	v_mfma_f32_16x16x4_f32 v[74:77], v200, v216, v[74:77]
	v_mfma_f32_16x16x4_f32 v[94:97], v201, v217, 0
	ds_read2st64_b32 v[212:213], v175 offset0:48 offset1:52
	ds_read2st64_b32 v[228:229], v176 offset0:140 offset1:141
	s_waitcnt lgkmcnt(12)
	v_mfma_f32_16x16x4_f32 v[74:77], v202, v218, v[74:77]
	v_mfma_f32_16x16x4_f32 v[94:97], v203, v219, v[94:97]
	ds_read2st64_b32 v[214:215], v175 offset0:56 offset1:60
	ds_read2st64_b32 v[230:231], v176 offset0:142 offset1:143
	s_waitcnt lgkmcnt(12)
	v_mfma_f32_16x16x4_f32 v[74:77], v204, v220, v[74:77]
	v_mfma_f32_16x16x4_f32 v[94:97], v205, v221, v[94:97]
	s_waitcnt lgkmcnt(10)
	v_mfma_f32_16x16x4_f32 v[74:77], v206, v222, v[74:77]
	v_mfma_f32_16x16x4_f32 v[94:97], v207, v223, v[94:97]
	s_waitcnt lgkmcnt(8)
	v_mfma_f32_16x16x4_f32 v[74:77], v208, v224, v[74:77]
	v_mfma_f32_16x16x4_f32 v[94:97], v209, v225, v[94:97]
	s_waitcnt lgkmcnt(6)
	v_mfma_f32_16x16x4_f32 v[74:77], v210, v226, v[74:77]
	v_mfma_f32_16x16x4_f32 v[94:97], v211, v227, v[94:97]
	s_waitcnt lgkmcnt(2)
	v_mfma_f32_16x16x4_f32 v[74:77], v212, v228, v[74:77]
	v_mfma_f32_16x16x4_f32 v[94:97], v213, v229, v[94:97]
	s_waitcnt lgkmcnt(0)
	v_mfma_f32_16x16x4_f32 v[74:77], v214, v230, v[74:77]
	v_mfma_f32_16x16x4_f32 v[94:97], v215, v231, v[94:97]
	s_nop 9
	v_pk_add_f32 v[74:75], v[74:75], v[94:95]
	v_add_co_u32_e32 v94, vcc, 0x30000, v92
	v_pk_add_f32 v[76:77], v[76:77], v[96:97]
	s_nop 0
	v_addc_co_u32_e32 v95, vcc, 0, v93, vcc
	global_store_dwordx4 v[94:95], v[74:77], off
	v_add_u32_e32 v94, 0x9000, v179
	ds_write2_b32 v94, v74, v75 offset1:16
	ds_write2_b32 v94, v76, v77 offset0:32 offset1:48
	s_branch .LBB0_504
.Lmy_cbw_502:
	s_waitcnt vmcnt(17)
	ds_write_b128 v81, v[18:21] offset:16384
	s_waitcnt vmcnt(16)
	ds_write_b128 v81, v[22:25] offset:16400
	v_lshl_add_u64 v[18:19], v[90:91], 0, s[72:73]
	s_mov_b64 s[16:17], 0xd8000
	v_lshl_add_u64 v[22:23], v[18:19], 0, s[16:17]
	v_add_co_u32_e32 v18, vcc, 0xd8000, v18
	v_lshl_add_u64 v[66:67], v[88:89], 0, s[10:11]
	s_nop 0
	v_addc_co_u32_e32 v19, vcc, 0, v19, vcc
	v_add_co_u32_e32 v66, vcc, 0xc0000, v66
	global_load_dwordx4 v[18:21], v[18:19], off
	s_nop 0
	global_load_dwordx4 v[22:25], v[22:23], off offset:16
	v_addc_co_u32_e32 v67, vcc, 0, v67, vcc
	global_load_dwordx4 v[66:69], v[66:67], off
.LBB0_504:
	s_min_u32 s2, s12, 0x74
	s_mulk_i32 s2, 0x6000
	s_lshl_b32 s10, s2, 2
	s_mov_b32 s11, s73
	s_waitcnt lgkmcnt(0)
	s_barrier
	s_and_b64 vcc, exec, s[6:7]
	s_cbranch_vccnz .Lmy_cbw_504
	ds_read2st64_b32 v[200:201], v175 offset0:64 offset1:68
	ds_read2st64_b32 v[216:217], v176 offset0:144 offset1:145
	ds_read2st64_b32 v[202:203], v175 offset0:72 offset1:76
	ds_read2st64_b32 v[218:219], v176 offset0:146 offset1:147
	ds_read2st64_b32 v[204:205], v175 offset0:80 offset1:84
	ds_read2st64_b32 v[220:221], v176 offset0:148 offset1:149
	ds_read2st64_b32 v[206:207], v175 offset0:88 offset1:92
	ds_read2st64_b32 v[222:223], v176 offset0:150 offset1:151
	ds_read2st64_b32 v[208:209], v175 offset0:96 offset1:100
	ds_read2st64_b32 v[224:225], v176 offset0:152 offset1:153
	ds_read2st64_b32 v[210:211], v175 offset0:104 offset1:108
	ds_read2st64_b32 v[226:227], v176 offset0:154 offset1:155
	s_waitcnt vmcnt(16)
	ds_write_b128 v81, v[30:33]
	ds_write_b128 v81, v[26:29] offset:16
	v_lshl_add_u64 v[26:27], v[90:91], 0, s[10:11]
	s_mov_b64 s[16:17], 0xf0000
	v_lshl_add_u64 v[28:29], v[26:27], 0, s[16:17]
	v_add_co_u32_e32 v26, vcc, 0xf0000, v26
	v_lshl_add_u64 v[74:75], v[88:89], 0, s[72:73]
	s_nop 0
	v_addc_co_u32_e32 v27, vcc, 0, v27, vcc
	v_add_co_u32_e32 v74, vcc, 0xd8000, v74
	global_load_dwordx4 v[30:33], v[26:27], off
	s_nop 0
	global_load_dwordx4 v[26:29], v[28:29], off offset:16
	v_addc_co_u32_e32 v75, vcc, 0, v75, vcc
	global_load_dwordx4 v[74:77], v[74:75], off
	s_waitcnt vmcnt(18) lgkmcnt(12)
	v_mfma_f32_16x16x4_f32 v[70:73], v200, v216, v[70:73]
	v_mfma_f32_16x16x4_f32 v[94:97], v201, v217, 0
	ds_read2st64_b32 v[212:213], v175 offset0:112 offset1:116
	ds_read2st64_b32 v[228:229], v176 offset0:156 offset1:157
	s_waitcnt lgkmcnt(12)
	v_mfma_f32_16x16x4_f32 v[70:73], v202, v218, v[70:73]
	v_mfma_f32_16x16x4_f32 v[94:97], v203, v219, v[94:97]
	ds_read2st64_b32 v[214:215], v175 offset0:120 offset1:124
	ds_read2st64_b32 v[230:231], v176 offset0:158 offset1:159
	s_waitcnt lgkmcnt(12)
	v_mfma_f32_16x16x4_f32 v[70:73], v204, v220, v[70:73]
	v_mfma_f32_16x16x4_f32 v[94:97], v205, v221, v[94:97]
	s_waitcnt lgkmcnt(10)
	v_mfma_f32_16x16x4_f32 v[70:73], v206, v222, v[70:73]
	v_mfma_f32_16x16x4_f32 v[94:97], v207, v223, v[94:97]
	s_waitcnt lgkmcnt(8)
	v_mfma_f32_16x16x4_f32 v[70:73], v208, v224, v[70:73]
	v_mfma_f32_16x16x4_f32 v[94:97], v209, v225, v[94:97]
	s_waitcnt lgkmcnt(6)
	v_mfma_f32_16x16x4_f32 v[70:73], v210, v226, v[70:73]
	v_mfma_f32_16x16x4_f32 v[94:97], v211, v227, v[94:97]
	s_waitcnt lgkmcnt(2)
	v_mfma_f32_16x16x4_f32 v[70:73], v212, v228, v[70:73]
	v_mfma_f32_16x16x4_f32 v[94:97], v213, v229, v[94:97]
	s_waitcnt lgkmcnt(0)
	v_mfma_f32_16x16x4_f32 v[70:73], v214, v230, v[70:73]
	v_mfma_f32_16x16x4_f32 v[94:97], v215, v231, v[94:97]
	s_nop 9
	v_pk_add_f32 v[70:71], v[70:71], v[94:95]
	v_add_co_u32_e32 v94, vcc, 0x48000, v92
	v_pk_add_f32 v[72:73], v[72:73], v[96:97]
	s_nop 0
	v_addc_co_u32_e32 v95, vcc, 0, v93, vcc
	global_store_dwordx4 v[94:95], v[70:73], off
	ds_write2_b32 v0, v70, v71 offset1:16
	ds_write2_b32 v0, v72, v73 offset0:32 offset1:48
	s_branch .LBB0_506
.Lmy_cbw_504:
	s_waitcnt vmcnt(16)
	ds_write_b128 v81, v[30:33]
	ds_write_b128 v81, v[26:29] offset:16
	v_lshl_add_u64 v[26:27], v[90:91], 0, s[10:11]
	s_mov_b64 s[16:17], 0xf0000
	v_lshl_add_u64 v[28:29], v[26:27], 0, s[16:17]
	v_add_co_u32_e32 v26, vcc, 0xf0000, v26
	v_lshl_add_u64 v[74:75], v[88:89], 0, s[72:73]
	s_nop 0
	v_addc_co_u32_e32 v27, vcc, 0, v27, vcc
	v_add_co_u32_e32 v74, vcc, 0xd8000, v74
	global_load_dwordx4 v[30:33], v[26:27], off
	s_nop 0
	global_load_dwordx4 v[26:29], v[28:29], off offset:16
	v_addc_co_u32_e32 v75, vcc, 0, v75, vcc
	global_load_dwordx4 v[74:77], v[74:75], off
.LBB0_506:
	s_min_u32 s2, s12, 0x73
	s_mulk_i32 s2, 0x6000
	s_lshl_b32 s72, s2, 2
	s_waitcnt lgkmcnt(0)
	s_barrier
	s_and_b64 vcc, exec, s[6:7]
	s_cbranch_vccnz .Lmy_cbw_506
	ds_read2st64_b32 v[200:201], v175 offset1:4
	ds_read2st64_b32 v[216:217], v176 offset0:128 offset1:129
	ds_read2st64_b32 v[202:203], v175 offset0:8 offset1:12
	ds_read2st64_b32 v[218:219], v176 offset0:130 offset1:131
	ds_read2st64_b32 v[204:205], v175 offset0:16 offset1:20
	ds_read2st64_b32 v[220:221], v176 offset0:132 offset1:133
	ds_read2st64_b32 v[206:207], v175 offset0:24 offset1:28
	ds_read2st64_b32 v[222:223], v176 offset0:134 offset1:135
	ds_read2st64_b32 v[208:209], v175 offset0:32 offset1:36
	ds_read2st64_b32 v[224:225], v176 offset0:136 offset1:137
	ds_read2st64_b32 v[210:211], v175 offset0:40 offset1:44
	ds_read2st64_b32 v[226:227], v176 offset0:138 offset1:139
	s_waitcnt vmcnt(17)
	ds_write_b128 v81, v[34:37] offset:16384
	s_waitcnt vmcnt(16)
	ds_write_b128 v81, v[38:41] offset:16400
	v_lshl_add_u64 v[34:35], v[90:91], 0, s[72:73]
	s_mov_b64 s[16:17], 0x108000
	v_lshl_add_u64 v[38:39], v[34:35], 0, s[16:17]
	v_add_co_u32_e32 v34, vcc, 0x108000, v34
	v_lshl_add_u64 v[70:71], v[88:89], 0, s[10:11]
	s_nop 0
	v_addc_co_u32_e32 v35, vcc, 0, v35, vcc
	v_add_co_u32_e32 v70, vcc, 0xf0000, v70
	global_load_dwordx4 v[34:37], v[34:35], off
	s_nop 0
	global_load_dwordx4 v[38:41], v[38:39], off offset:16
	v_addc_co_u32_e32 v71, vcc, 0, v71, vcc
	global_load_dwordx4 v[70:73], v[70:71], off
	s_waitcnt vmcnt(18) lgkmcnt(12)
	v_mfma_f32_16x16x4_f32 v[62:65], v200, v216, v[62:65]
	v_mfma_f32_16x16x4_f32 v[94:97], v201, v217, 0
	ds_read2st64_b32 v[212:213], v175 offset0:48 offset1:52
	ds_read2st64_b32 v[228:229], v176 offset0:140 offset1:141
	s_waitcnt lgkmcnt(12)
	v_mfma_f32_16x16x4_f32 v[62:65], v202, v218, v[62:65]
	v_mfma_f32_16x16x4_f32 v[94:97], v203, v219, v[94:97]
	ds_read2st64_b32 v[214:215], v175 offset0:56 offset1:60
	ds_read2st64_b32 v[230:231], v176 offset0:142 offset1:143
	s_waitcnt lgkmcnt(12)
	v_mfma_f32_16x16x4_f32 v[62:65], v204, v220, v[62:65]
	v_mfma_f32_16x16x4_f32 v[94:97], v205, v221, v[94:97]
	s_waitcnt lgkmcnt(10)
	v_mfma_f32_16x16x4_f32 v[62:65], v206, v222, v[62:65]
	v_mfma_f32_16x16x4_f32 v[94:97], v207, v223, v[94:97]
	s_waitcnt lgkmcnt(8)
	v_mfma_f32_16x16x4_f32 v[62:65], v208, v224, v[62:65]
	v_mfma_f32_16x16x4_f32 v[94:97], v209, v225, v[94:97]
	s_waitcnt lgkmcnt(6)
	v_mfma_f32_16x16x4_f32 v[62:65], v210, v226, v[62:65]
	v_mfma_f32_16x16x4_f32 v[94:97], v211, v227, v[94:97]
	s_waitcnt lgkmcnt(2)
	v_mfma_f32_16x16x4_f32 v[62:65], v212, v228, v[62:65]
	v_mfma_f32_16x16x4_f32 v[94:97], v213, v229, v[94:97]
	s_waitcnt lgkmcnt(0)
	v_mfma_f32_16x16x4_f32 v[62:65], v214, v230, v[62:65]
	v_mfma_f32_16x16x4_f32 v[94:97], v215, v231, v[94:97]
	s_nop 9
	v_pk_add_f32 v[62:63], v[62:63], v[94:95]
	v_add_co_u32_e32 v94, vcc, 0x60000, v92
	v_pk_add_f32 v[64:65], v[64:65], v[96:97]
	s_nop 0
	v_addc_co_u32_e32 v95, vcc, 0, v93, vcc
	global_store_dwordx4 v[94:95], v[62:65], off
	v_add_u32_e32 v94, 0x9000, v179
	ds_write2_b32 v94, v62, v63 offset1:16
	ds_write2_b32 v94, v64, v65 offset0:32 offset1:48
	s_branch .LBB0_508
.Lmy_cbw_506:
	s_waitcnt vmcnt(17)
	ds_write_b128 v81, v[34:37] offset:16384
	s_waitcnt vmcnt(16)
	ds_write_b128 v81, v[38:41] offset:16400
	v_lshl_add_u64 v[34:35], v[90:91], 0, s[72:73]
	s_mov_b64 s[16:17], 0x108000
	v_lshl_add_u64 v[38:39], v[34:35], 0, s[16:17]
	v_add_co_u32_e32 v34, vcc, 0x108000, v34
	v_lshl_add_u64 v[70:71], v[88:89], 0, s[10:11]
	s_nop 0
	v_addc_co_u32_e32 v35, vcc, 0, v35, vcc
	v_add_co_u32_e32 v70, vcc, 0xf0000, v70
	global_load_dwordx4 v[34:37], v[34:35], off
	s_nop 0
	global_load_dwordx4 v[38:41], v[38:39], off offset:16
	v_addc_co_u32_e32 v71, vcc, 0, v71, vcc
	global_load_dwordx4 v[70:73], v[70:71], off
.LBB0_508:
	s_min_u32 s2, s12, 0x72
	s_mul_i32 s10, s2, 0x18000
	s_mov_b32 s11, s73
	s_waitcnt lgkmcnt(0)
	s_barrier
	s_and_b64 vcc, exec, s[6:7]
	s_cbranch_vccnz .Lmy_cbw_508
	ds_read2st64_b32 v[200:201], v175 offset0:64 offset1:68
	ds_read2st64_b32 v[216:217], v176 offset0:144 offset1:145
	ds_read2st64_b32 v[202:203], v175 offset0:72 offset1:76
	ds_read2st64_b32 v[218:219], v176 offset0:146 offset1:147
	ds_read2st64_b32 v[204:205], v175 offset0:80 offset1:84
	ds_read2st64_b32 v[220:221], v176 offset0:148 offset1:149
	ds_read2st64_b32 v[206:207], v175 offset0:88 offset1:92
	ds_read2st64_b32 v[222:223], v176 offset0:150 offset1:151
	ds_read2st64_b32 v[208:209], v175 offset0:96 offset1:100
	ds_read2st64_b32 v[224:225], v176 offset0:152 offset1:153
	ds_read2st64_b32 v[210:211], v175 offset0:104 offset1:108
	ds_read2st64_b32 v[226:227], v176 offset0:154 offset1:155
	s_waitcnt vmcnt(16)
	ds_write_b128 v81, v[46:49]
	ds_write_b128 v81, v[42:45] offset:16
	v_lshl_add_u64 v[42:43], v[90:91], 0, s[10:11]
	s_mov_b64 s[10:11], 0x120000
	v_lshl_add_u64 v[44:45], v[42:43], 0, s[10:11]
	v_add_co_u32_e32 v42, vcc, 0x120000, v42
	v_lshl_add_u64 v[62:63], v[88:89], 0, s[72:73]
	s_nop 0
	v_addc_co_u32_e32 v43, vcc, 0, v43, vcc
	v_add_co_u32_e32 v62, vcc, 0x108000, v62
	global_load_dwordx4 v[46:49], v[42:43], off
	s_nop 0
	global_load_dwordx4 v[42:45], v[44:45], off offset:16
	v_addc_co_u32_e32 v63, vcc, 0, v63, vcc
	global_load_dwordx4 v[62:65], v[62:63], off
	s_waitcnt vmcnt(18) lgkmcnt(12)
	v_mfma_f32_16x16x4_f32 v[54:57], v200, v216, v[54:57]
	v_mfma_f32_16x16x4_f32 v[94:97], v201, v217, 0
	ds_read2st64_b32 v[212:213], v175 offset0:112 offset1:116
	ds_read2st64_b32 v[228:229], v176 offset0:156 offset1:157
	s_waitcnt lgkmcnt(12)
	v_mfma_f32_16x16x4_f32 v[54:57], v202, v218, v[54:57]
	v_mfma_f32_16x16x4_f32 v[94:97], v203, v219, v[94:97]
	ds_read2st64_b32 v[214:215], v175 offset0:120 offset1:124
	ds_read2st64_b32 v[230:231], v176 offset0:158 offset1:159
	s_waitcnt lgkmcnt(12)
	v_mfma_f32_16x16x4_f32 v[54:57], v204, v220, v[54:57]
	v_mfma_f32_16x16x4_f32 v[94:97], v205, v221, v[94:97]
	s_waitcnt lgkmcnt(10)
	v_mfma_f32_16x16x4_f32 v[54:57], v206, v222, v[54:57]
	v_mfma_f32_16x16x4_f32 v[94:97], v207, v223, v[94:97]
	s_waitcnt lgkmcnt(8)
	v_mfma_f32_16x16x4_f32 v[54:57], v208, v224, v[54:57]
	v_mfma_f32_16x16x4_f32 v[94:97], v209, v225, v[94:97]
	s_waitcnt lgkmcnt(6)
	v_mfma_f32_16x16x4_f32 v[54:57], v210, v226, v[54:57]
	v_mfma_f32_16x16x4_f32 v[94:97], v211, v227, v[94:97]
	s_waitcnt lgkmcnt(2)
	v_mfma_f32_16x16x4_f32 v[54:57], v212, v228, v[54:57]
	v_mfma_f32_16x16x4_f32 v[94:97], v213, v229, v[94:97]
	s_waitcnt lgkmcnt(0)
	v_mfma_f32_16x16x4_f32 v[54:57], v214, v230, v[54:57]
	v_mfma_f32_16x16x4_f32 v[94:97], v215, v231, v[94:97]
	s_nop 9
	v_pk_add_f32 v[54:55], v[54:55], v[94:95]
	v_add_co_u32_e32 v94, vcc, 0x78000, v92
	v_pk_add_f32 v[56:57], v[56:57], v[96:97]
	s_nop 0
	v_addc_co_u32_e32 v95, vcc, 0, v93, vcc
	global_store_dwordx4 v[94:95], v[54:57], off
	ds_write2_b32 v0, v54, v55 offset1:16
	ds_write2_b32 v0, v56, v57 offset0:32 offset1:48
	s_branch .LBB0_510
.Lmy_cbw_508:
	s_waitcnt vmcnt(16)
	ds_write_b128 v81, v[46:49]
	ds_write_b128 v81, v[42:45] offset:16
	v_lshl_add_u64 v[42:43], v[90:91], 0, s[10:11]
	s_mov_b64 s[10:11], 0x120000
	v_lshl_add_u64 v[44:45], v[42:43], 0, s[10:11]
	v_add_co_u32_e32 v42, vcc, 0x120000, v42
	v_lshl_add_u64 v[62:63], v[88:89], 0, s[72:73]
	s_nop 0
	v_addc_co_u32_e32 v43, vcc, 0, v43, vcc
	v_add_co_u32_e32 v62, vcc, 0x108000, v62
	global_load_dwordx4 v[46:49], v[42:43], off
	s_nop 0
	global_load_dwordx4 v[42:45], v[44:45], off offset:16
	v_addc_co_u32_e32 v63, vcc, 0, v63, vcc
	global_load_dwordx4 v[62:65], v[62:63], off
